# P24: attention item prologue requests K/V chunk 1 right behind chunk 0 (chunk 0 staged through v146..161, LDS stores wait vmcnt(4))
# speedup vs baseline: 1.0230x; 1.0035x over previous
.LBB0_656:
	v_ashrrev_i32_e32 v191, 4, v4
	v_and_b32_e32 v8, 15, v4
	v_ashrrev_i32_e32 v205, 3, v4
	v_and_b32_e32 v9, 7, v4
	v_mad_i64_i32 v[4:5], s[48:49], s44, v191, 0
	v_lshl_add_u64 v[4:5], v[4:5], 1, s[0:1]
	v_lshlrev_b32_e32 v0, 4, v8
	v_lshl_add_u64 v[4:5], v[4:5], 0, v[0:1]
	global_load_dwordx4 v[146:149], v[4:5], off
	v_mad_i64_i32 v[4:5], s[48:49], s38, v205, 0
	v_lshl_add_u64 v[4:5], v[4:5], 1, s[30:31]
	v_lshlrev_b32_e32 v6, 4, v9
	v_mov_b32_e32 v7, v1
	v_lshl_add_u64 v[4:5], v[4:5], 0, v[6:7]
	v_add_u32_e32 v206, 32, v191
	global_load_dwordx4 v[150:153], v[4:5], off
	v_mad_i64_i32 v[4:5], s[44:45], s44, v206, 0
	v_lshl_add_u64 v[4:5], v[4:5], 1, s[0:1]
	v_lshl_add_u64 v[4:5], v[4:5], 0, v[0:1]
	v_add_u32_e32 v207, 64, v205
	global_load_dwordx4 v[154:157], v[4:5], off
	v_mad_i64_i32 v[4:5], s[0:1], s38, v207, 0
	v_lshl_add_u64 v[4:5], v[4:5], 1, s[30:31]
	v_lshl_add_u64 v[4:5], v[4:5], 0, v[6:7]
	global_load_dwordx4 v[158:161], v[4:5], off
	s_and_b64 s[0:1], s[40:41], exec
	s_movk_i32 s1, 0x88
	v_mul_lo_u32 v5, v205, s1
	s_cselect_b32 s0, 0, 4
	v_mul_lo_u32 v4, v191, s78
	v_add_u32_e32 v5, 0, v5
	s_add_i32 s86, s68, s0
	v_add_u32_e32 v4, 0, v4
	v_add_u32_e32 v211, v5, v6
	v_lshlrev_b32_e32 v208, 3, v8
	v_lshlrev_b32_e32 v209, 3, v9
	v_add_u32_e32 v210, v4, v0
	s_cmp_lt_i32 s86, 2
	v_add_u32_e32 v212, 0x4400, v211
	v_add_u32_e32 v213, 0x6600, v211
	s_cbranch_scc1 .Lattn_one_chunk
	s_cmp_lt_i32 s68, 2
	s_mov_b64 s[38:39], -1
	s_cbranch_scc0 .LBB0_659
	s_sub_i32 s60, 64, s47
	s_lshl_b64 s[0:1], s[60:61], 10
	s_add_u32 s0, s82, s0
	s_addc_u32 s1, s83, s1
	s_lshl_b64 s[30:31], s[60:61], 1
	s_add_u32 s30, s84, s30
	s_addc_u32 s31, s85, s31
	s_mov_b64 s[38:39], 0

.LBB0_662:
	v_mad_i64_i32 v[4:5], s[48:49], s44, v191, 0
	v_lshl_add_u64 v[4:5], v[4:5], 1, s[0:1]
	v_lshlrev_b32_e32 v0, 1, v208
	v_lshl_add_u64 v[4:5], v[4:5], 0, v[0:1]
	global_load_dwordx4 v[114:117], v[4:5], off
	v_mad_i64_i32 v[4:5], s[48:49], s38, v205, 0
	v_lshl_add_u64 v[4:5], v[4:5], 1, s[30:31]
	v_lshlrev_b32_e32 v6, 1, v209
	v_mov_b32_e32 v7, v1
	v_lshl_add_u64 v[4:5], v[4:5], 0, v[6:7]
	global_load_dwordx4 v[118:121], v[4:5], off
	v_mad_i64_i32 v[4:5], s[44:45], s44, v206, 0
	v_lshl_add_u64 v[4:5], v[4:5], 1, s[0:1]
	v_lshl_add_u64 v[4:5], v[4:5], 0, v[0:1]
	global_load_dwordx4 v[122:125], v[4:5], off
	v_mad_i64_i32 v[4:5], s[0:1], s38, v207, 0
	v_lshl_add_u64 v[4:5], v[4:5], 1, s[30:31]
	v_lshl_add_u64 v[4:5], v[4:5], 0, v[6:7]
	global_load_dwordx4 v[126:129], v[4:5], off
	s_waitcnt lgkmcnt(0)
	s_barrier
	s_waitcnt vmcnt(4)
	ds_write_b128 v210, v[146:149]
	ds_write2_b64 v212, v[150:151], v[152:153] offset1:1
	ds_write_b128 v210, v[154:157] offset:8704
	ds_write2_b64 v213, v[158:159], v[160:161] offset1:1
	s_branch .LBB0_663
.Lattn_one_chunk:
	s_waitcnt lgkmcnt(0)
	s_barrier
	s_waitcnt vmcnt(0)
	ds_write_b128 v210, v[146:149]
	ds_write2_b64 v212, v[150:151], v[152:153] offset1:1
	ds_write_b128 v210, v[154:157] offset:8704
	ds_write2_b64 v213, v[158:159], v[160:161] offset1:1
